# v24 + counted LDS waits in the GLA scan step: the blanket lgkmcnt(0) before each of the 9 MFMA groups removed so the per-operand counted waits take effect
# baseline (speedup 1.0000x reference)
; #define LAS __attribute__((address_space(3)))
; __device__ __forceinline__ void gla_scan_item(ArgsP a, int item, LAS unsigned char* lds) {
;     ...
;         bf16x8 vf[2];
; #pragma unroll
;         for (int ks = 0; ks < 2; ++ks) { s16x4 t0, t1;
;             asm volatile("ds_read_b64_tr_b16 %0, %1" : "=&v"(t0) : "v"(vaddr + (unsigned)((32 * ks) * 288)) : "memory");
;             asm volatile("ds_read_b64_tr_b16 %0, %1" : "=&v"(t1) : "v"(vaddr + (unsigned)((32 * ks + 4) * 288)) : "memory");
;             asm volatile("s_waitcnt lgkmcnt(0)" ::: "memory");
;             vf[ks] = (bf16x8){t0[0], t0[1], t0[2], t0[3], t1[0], t1[1], t1[2], t1[3]}; }
;         f32x4 o[4];
; #pragma unroll
;         for (int it = 0; it < 4; ++it) o[it] = (f32x4){0.f, 0.f, 0.f, 0.f};
;     ...
;         { bf16x8 av[4][2];
; #pragma unroll
;           for (int it = 0; it < 4; ++it)
; #pragma unroll
;               for (int ks = 0; ks < 2; ++ks) av[it][ks] = *(const LAS bf16x8*)(atl + (16 * it + fr) * 144 + (32 * ks + 8 * g4) * 2);
;           LWAIT();
; #pragma unroll
;           for (int ks = 0; ks < 2; ++ks)
; #pragma unroll
;               for (int it = 0; it < 4; ++it) o[it] = __builtin_amdgcn_mfma_f32_16x16x32_bf16(av[it][ks], vf[ks], o[it], 0, 0, 0); }
; #pragma unroll
;         for (int k2 = 0; k2 < 4; ++k2) { u32x2 lo[2][4], hi2[2][4];
; #pragma unroll
;             for (int q = 0; q < 2; ++q)
; #pragma unroll
;                 for (int it = 0; it < 4; ++it) { const LAS unsigned char* qp = qdl + (16 * it + fr) * 528 + (32 * (2 * k2 + q) + 4 * g4) * 2; lo[q][it] = *(const LAS u32x2*)qp; hi2[q][it] = *(const LAS u32x2*)(qp + 32); }
;             bf16x8 bfr[2];
; #pragma unroll
;             for (int q = 0; q < 2; ++q) { const int kk = 2 * k2 + q; u32x4 bw; bw.x = cvt_pk_bf16(S[2 * kk][0], S[2 * kk][1]); bw.y = cvt_pk_bf16(S[2 * kk][2], S[2 * kk][3]); bw.z = cvt_pk_bf16(S[2 * kk + 1][0], S[2 * kk + 1][1]); bw.w = cvt_pk_bf16(S[2 * kk + 1][2], S[2 * kk + 1][3]); bfr[q] = __builtin_bit_cast(bf16x8, bw); }
;             LWAIT();
; #pragma unroll
;             for (int q = 0; q < 2; ++q)
; #pragma unroll
;                 for (int it = 0; it < 4; ++it) { const u32x4 aw = {lo[q][it].x, lo[q][it].y, hi2[q][it].x, hi2[q][it].y}; o[it] = __builtin_amdgcn_mfma_f32_16x16x32_bf16(__builtin_bit_cast(bf16x8, aw), bfr[q], o[it], 0, 0, 0); } }
.LBB0_1405:
	ds_read_b64_tr_b16 v[116:117], v152
	ds_read_b64_tr_b16 v[118:119], v156
	s_waitcnt lgkmcnt(0)
	ds_read_b64_tr_b16 v[112:113], v159
	ds_read_b64_tr_b16 v[114:115], v164
	s_waitcnt lgkmcnt(0)
	ds_read_b128 v[120:123], v177
	ds_read_b128 v[124:127], v177 offset:64
	ds_read_b128 v[128:131], v177 offset:2304
	ds_read_b128 v[132:135], v177 offset:2368
	ds_read_b128 v[180:183], v177 offset:4608
	ds_read_b128 v[184:187], v177 offset:4672
	ds_read_b128 v[188:191], v177 offset:6912
	ds_read_b128 v[192:195], v177 offset:6976
	s_cmp_gt_u32 s35, 3
	s_cselect_b32 s17, 39, 3
	s_add_i32 s17, s17, s22
	s_sub_i32 s17, s17, 38
	s_and_b64 s[18:19], s[4:5], exec
	s_cselect_b32 s17, s35, s17
	s_lshl_b32 s17, s17, 6
	s_add_i32 s18, s17, s42
	s_waitcnt lgkmcnt(7)
	v_mfma_f32_16x16x32_bf16 v[120:123], v[120:123], v[116:119], 0
	v_add_u32_e32 v179, 0x2000, v178
	v_add_u32_e32 v204, 0x4000, v178
	v_add_u32_e32 v205, 0x6000, v178
	s_waitcnt lgkmcnt(5)
	v_mfma_f32_16x16x32_bf16 v[128:131], v[128:131], v[116:119], 0
	s_waitcnt lgkmcnt(3)
	v_mfma_f32_16x16x32_bf16 v[180:183], v[180:183], v[116:119], 0
	s_waitcnt lgkmcnt(1)
	v_mfma_f32_16x16x32_bf16 v[188:191], v[188:191], v[116:119], 0
	v_mfma_f32_16x16x32_bf16 v[120:123], v[124:127], v[112:115], v[120:123]
	v_mfma_f32_16x16x32_bf16 v[124:127], v[132:135], v[112:115], v[128:131]
	v_mfma_f32_16x16x32_bf16 v[128:131], v[184:187], v[112:115], v[180:183]
	ds_read2_b64 v[184:187], v179 offset0:32 offset1:36
	s_waitcnt lgkmcnt(1)
	v_mfma_f32_16x16x32_bf16 v[132:135], v[192:195], v[112:115], v[188:191]
	ds_read2_b64 v[180:183], v178 offset1:4
	s_nop 1
	ds_read2_b64 v[188:191], v204 offset0:64 offset1:68
	ds_read2_b64 v[192:195], v205 offset0:96 offset1:100
	ds_read2_b64 v[196:199], v178 offset0:8 offset1:12
	ds_read2_b64 v[200:203], v179 offset0:40 offset1:44
	ds_read2_b64 v[216:219], v204 offset0:72 offset1:76
	ds_read2_b64 v[220:223], v205 offset0:104 offset1:108
	v_cvt_pk_bf16_f32 v224, v80, v81
	v_cvt_pk_bf16_f32 v225, v82, v83
	v_cvt_pk_bf16_f32 v226, v76, v77
	v_cvt_pk_bf16_f32 v227, v78, v79
	v_cvt_pk_bf16_f32 v228, v72, v73
	v_cvt_pk_bf16_f32 v229, v74, v75
	v_cvt_pk_bf16_f32 v230, v68, v69
	v_cvt_pk_bf16_f32 v231, v70, v71
	s_waitcnt lgkmcnt(6)
	v_mfma_f32_16x16x32_bf16 v[120:123], v[180:183], v[224:227], v[120:123]
	v_mfma_f32_16x16x32_bf16 v[124:127], v[184:187], v[224:227], v[124:127]
	s_waitcnt lgkmcnt(5)
	v_mfma_f32_16x16x32_bf16 v[128:131], v[188:191], v[224:227], v[128:131]
	s_waitcnt lgkmcnt(4)
	v_mfma_f32_16x16x32_bf16 v[132:135], v[192:195], v[224:227], v[132:135]
	s_waitcnt lgkmcnt(3)
	v_mfma_f32_16x16x32_bf16 v[120:123], v[196:199], v[228:231], v[120:123]
	s_waitcnt lgkmcnt(2)
	v_mfma_f32_16x16x32_bf16 v[124:127], v[200:203], v[228:231], v[124:127]
	s_waitcnt lgkmcnt(1)
	v_mfma_f32_16x16x32_bf16 v[128:131], v[216:219], v[228:231], v[128:131]
	s_waitcnt lgkmcnt(0)
	v_mfma_f32_16x16x32_bf16 v[132:135], v[220:223], v[228:231], v[132:135]
	ds_read2_b64 v[180:183], v178 offset0:16 offset1:20
	ds_read2_b64 v[184:187], v179 offset0:48 offset1:52
	ds_read2_b64 v[188:191], v204 offset0:80 offset1:84
	ds_read2_b64 v[192:195], v205 offset0:112 offset1:116
	ds_read2_b64 v[196:199], v178 offset0:24 offset1:28
	ds_read2_b64 v[200:203], v179 offset0:56 offset1:60
	ds_read2_b64 v[216:219], v204 offset0:88 offset1:92
	ds_read2_b64 v[220:223], v205 offset0:120 offset1:124
	v_cvt_pk_bf16_f32 v224, v60, v61
	v_cvt_pk_bf16_f32 v225, v62, v63
	v_cvt_pk_bf16_f32 v226, v48, v49
	v_cvt_pk_bf16_f32 v227, v50, v51
	v_cvt_pk_bf16_f32 v228, v88, v89
	v_cvt_pk_bf16_f32 v229, v90, v91
	v_cvt_pk_bf16_f32 v230, v92, v93
	v_cvt_pk_bf16_f32 v231, v94, v95
	s_waitcnt lgkmcnt(7)
	v_mfma_f32_16x16x32_bf16 v[120:123], v[180:183], v[224:227], v[120:123]
	s_waitcnt lgkmcnt(6)
	v_mfma_f32_16x16x32_bf16 v[124:127], v[184:187], v[224:227], v[124:127]
	s_waitcnt lgkmcnt(5)
	v_mfma_f32_16x16x32_bf16 v[128:131], v[188:191], v[224:227], v[128:131]
	s_waitcnt lgkmcnt(4)
	v_mfma_f32_16x16x32_bf16 v[132:135], v[192:195], v[224:227], v[132:135]
	s_waitcnt lgkmcnt(3)
	v_mfma_f32_16x16x32_bf16 v[120:123], v[196:199], v[228:231], v[120:123]
	s_waitcnt lgkmcnt(2)
	v_mfma_f32_16x16x32_bf16 v[124:127], v[200:203], v[228:231], v[124:127]
	s_waitcnt lgkmcnt(1)
	v_mfma_f32_16x16x32_bf16 v[128:131], v[216:219], v[228:231], v[128:131]
	s_waitcnt lgkmcnt(0)
	v_mfma_f32_16x16x32_bf16 v[132:135], v[220:223], v[228:231], v[132:135]
	ds_read2_b64 v[180:183], v178 offset0:32 offset1:36
	ds_read2_b64 v[184:187], v179 offset0:64 offset1:68
	ds_read2_b64 v[188:191], v204 offset0:96 offset1:100
	ds_read2_b64 v[192:195], v205 offset0:128 offset1:132
	ds_read2_b64 v[196:199], v178 offset0:40 offset1:44
	ds_read2_b64 v[200:203], v179 offset0:72 offset1:76
	ds_read2_b64 v[216:219], v204 offset0:104 offset1:108
	ds_read2_b64 v[220:223], v205 offset0:136 offset1:140
	v_cvt_pk_bf16_f32 v224, v96, v97
	v_cvt_pk_bf16_f32 v225, v98, v99
	v_cvt_pk_bf16_f32 v226, v100, v101
	v_cvt_pk_bf16_f32 v227, v102, v103
	v_cvt_pk_bf16_f32 v228, v104, v105
	v_cvt_pk_bf16_f32 v229, v106, v107
	v_cvt_pk_bf16_f32 v230, v108, v109
	v_cvt_pk_bf16_f32 v231, v110, v111
	s_waitcnt lgkmcnt(7)
	v_mfma_f32_16x16x32_bf16 v[120:123], v[180:183], v[224:227], v[120:123]
	s_waitcnt lgkmcnt(6)
	v_mfma_f32_16x16x32_bf16 v[124:127], v[184:187], v[224:227], v[124:127]
	s_waitcnt lgkmcnt(5)
	v_mfma_f32_16x16x32_bf16 v[128:131], v[188:191], v[224:227], v[128:131]
	s_waitcnt lgkmcnt(4)
	v_mfma_f32_16x16x32_bf16 v[132:135], v[192:195], v[224:227], v[132:135]
	s_waitcnt lgkmcnt(3)
	v_mfma_f32_16x16x32_bf16 v[120:123], v[196:199], v[228:231], v[120:123]
	s_waitcnt lgkmcnt(2)
; #define LAS __attribute__((address_space(3)))
; __device__ __forceinline__ unsigned cvt_pk_bf16(float lo, float hi) { unsigned r; asm volatile("v_cvt_pk_bf16_f32 %0, %1, %2" : "=v"(r) : "v"(lo), "v"(hi)); return r; }
; #define LWAIT() do { asm volatile("s_waitcnt lgkmcnt(0)" ::: "memory"); __builtin_amdgcn_sched_barrier(0); } while (0)
; __device__ __forceinline__ void gla_scan_item(ArgsP a, int item, LAS unsigned char* lds) {
;     ...
;         for (int k2 = 0; k2 < 4; ++k2) { u32x2 lo[2][4], hi2[2][4];
; #pragma unroll
;             for (int q = 0; q < 2; ++q)
; #pragma unroll
;                 for (int it = 0; it < 4; ++it) { const LAS unsigned char* qp = qdl + (16 * it + fr) * 528 + (32 * (2 * k2 + q) + 4 * g4) * 2; lo[q][it] = *(const LAS u32x2*)qp; hi2[q][it] = *(const LAS u32x2*)(qp + 32); }
;             bf16x8 bfr[2];
; #pragma unroll
;             for (int q = 0; q < 2; ++q) { const int kk = 2 * k2 + q; u32x4 bw; bw.x = cvt_pk_bf16(S[2 * kk][0], S[2 * kk][1]); bw.y = cvt_pk_bf16(S[2 * kk][2], S[2 * kk][3]); bw.z = cvt_pk_bf16(S[2 * kk + 1][0], S[2 * kk + 1][1]); bw.w = cvt_pk_bf16(S[2 * kk + 1][2], S[2 * kk + 1][3]); bfr[q] = __builtin_bit_cast(bf16x8, bw); }
;             LWAIT();
; #pragma unroll
;             for (int q = 0; q < 2; ++q)
; #pragma unroll
;                 for (int it = 0; it < 4; ++it) { const u32x4 aw = {lo[q][it].x, lo[q][it].y, hi2[q][it].x, hi2[q][it].y}; o[it] = __builtin_amdgcn_mfma_f32_16x16x32_bf16(__builtin_bit_cast(bf16x8, aw), bfr[q], o[it], 0, 0, 0); } }
; #pragma unroll
;         for (int m4 = 0; m4 < 4; ++m4) { bf16x8 av[4][2]; f32x4 dv4[4];
; #pragma unroll
;             for (int q = 0; q < 4; ++q) { const int mt = 4 * m4 + q; dv4[q] = *(const LAS f32x4*)(decl + 16 * mt + 4 * g4);
; #pragma unroll
;                 for (int ks = 0; ks < 2; ++ks) av[q][ks] = *(const LAS bf16x8*)(ktl + (16 * mt + fr) * 144 + (32 * ks + 8 * g4) * 2); }
;             LWAIT();
; #pragma unroll
;             for (int q = 0; q < 4; ++q) S[4 * m4 + q] = S[4 * m4 + q] * dv4[q];
; #pragma unroll
;             for (int ks = 0; ks < 2; ++ks)
; #pragma unroll
;                 for (int q = 0; q < 4; ++q) S[4 * m4 + q] = __builtin_amdgcn_mfma_f32_16x16x32_bf16(av[q][ks], vf[ks], S[4 * m4 + q], 0, 0, 0); }
	v_mfma_f32_16x16x32_bf16 v[124:127], v[200:203], v[228:231], v[124:127]
	s_waitcnt lgkmcnt(1)
	v_mfma_f32_16x16x32_bf16 v[128:131], v[216:219], v[228:231], v[128:131]
	s_waitcnt lgkmcnt(0)
	v_mfma_f32_16x16x32_bf16 v[132:135], v[220:223], v[228:231], v[132:135]
	ds_read2_b64 v[180:183], v178 offset0:48 offset1:52
	ds_read2_b64 v[184:187], v179 offset0:80 offset1:84
	ds_read2_b64 v[188:191], v204 offset0:112 offset1:116
	ds_read2_b64 v[192:195], v205 offset0:144 offset1:148
	ds_read2_b64 v[196:199], v178 offset0:56 offset1:60
	ds_read2_b64 v[200:203], v179 offset0:88 offset1:92
	ds_read2_b64 v[216:219], v204 offset0:120 offset1:124
	ds_read2_b64 v[220:223], v205 offset0:152 offset1:156
	v_cvt_pk_bf16_f32 v224, v84, v85
	v_cvt_pk_bf16_f32 v225, v86, v87
	v_cvt_pk_bf16_f32 v226, v52, v53
	v_cvt_pk_bf16_f32 v227, v54, v55
	v_cvt_pk_bf16_f32 v228, v56, v57
	v_cvt_pk_bf16_f32 v229, v58, v59
	v_cvt_pk_bf16_f32 v230, v64, v65
	v_cvt_pk_bf16_f32 v231, v66, v67
	s_waitcnt lgkmcnt(7)
	v_mfma_f32_16x16x32_bf16 v[120:123], v[180:183], v[224:227], v[120:123]
	v_add_u32_e32 v179, 0, v157
	v_add_u32_e32 v179, 0x18000, v179
	v_add_u32_e32 v204, v158, v165
	s_waitcnt lgkmcnt(6)
	v_mfma_f32_16x16x32_bf16 v[124:127], v[184:187], v[224:227], v[124:127]
	s_waitcnt lgkmcnt(5)
	v_mfma_f32_16x16x32_bf16 v[180:183], v[188:191], v[224:227], v[128:131]
	s_waitcnt lgkmcnt(4)
	v_mfma_f32_16x16x32_bf16 v[184:187], v[192:195], v[224:227], v[132:135]
	s_waitcnt lgkmcnt(3)
	v_mfma_f32_16x16x32_bf16 v[132:135], v[196:199], v[228:231], v[120:123]
	s_waitcnt lgkmcnt(2)
	v_mfma_f32_16x16x32_bf16 v[128:131], v[200:203], v[228:231], v[124:127]
	s_waitcnt lgkmcnt(1)
	v_mfma_f32_16x16x32_bf16 v[124:127], v[216:219], v[228:231], v[180:183]
	s_waitcnt lgkmcnt(0)
	v_mfma_f32_16x16x32_bf16 v[120:123], v[220:223], v[228:231], v[184:187]
	s_nop 0
	ds_read_b128 v[180:183], v179
	s_nop 0
	ds_read_b128 v[184:187], v204 offset:33792
	ds_read_b128 v[188:191], v204 offset:33856
	ds_read_b128 v[192:195], v179 offset:64
	ds_read_b128 v[196:199], v204 offset:36096
	ds_read_b128 v[200:203], v204 offset:36160
	ds_read_b128 v[216:219], v179 offset:128
	ds_read_b128 v[220:223], v204 offset:38400
	ds_read_b128 v[224:227], v204 offset:38464
	ds_read_b128 v[228:231], v179 offset:192
	ds_read_b128 v[232:235], v204 offset:40704
	ds_read_b128 v[236:239], v204 offset:40768
	s_waitcnt lgkmcnt(11)
	v_pk_mul_f32 v[80:81], v[80:81], v[180:181]
	v_pk_mul_f32 v[82:83], v[82:83], v[182:183]
	s_waitcnt lgkmcnt(8)
	v_pk_mul_f32 v[76:77], v[76:77], v[192:193]
	v_pk_mul_f32 v[78:79], v[78:79], v[194:195]
	s_waitcnt lgkmcnt(5)
	v_pk_mul_f32 v[72:73], v[72:73], v[216:217]
	v_pk_mul_f32 v[74:75], v[74:75], v[218:219]
	s_waitcnt lgkmcnt(2)
	v_pk_mul_f32 v[68:69], v[68:69], v[228:229]
	v_pk_mul_f32 v[70:71], v[70:71], v[230:231]
	v_mfma_f32_16x16x32_bf16 v[80:83], v[184:187], v[116:119], v[80:83]
	v_mfma_f32_16x16x32_bf16 v[76:79], v[196:199], v[116:119], v[76:79]
	v_mfma_f32_16x16x32_bf16 v[72:75], v[220:223], v[116:119], v[72:75]
	s_waitcnt lgkmcnt(1)
	v_mfma_f32_16x16x32_bf16 v[68:71], v[232:235], v[116:119], v[68:71]
	v_mfma_f32_16x16x32_bf16 v[80:83], v[188:191], v[112:115], v[80:83]
	v_mfma_f32_16x16x32_bf16 v[76:79], v[200:203], v[112:115], v[76:79]
	v_mfma_f32_16x16x32_bf16 v[72:75], v[224:227], v[112:115], v[72:75]
	s_waitcnt lgkmcnt(0)
	v_mfma_f32_16x16x32_bf16 v[68:71], v[236:239], v[112:115], v[68:71]
	ds_read_b128 v[180:183], v179 offset:256
	ds_read_b128 v[184:187], v204 offset:43008
	ds_read_b128 v[188:191], v204 offset:43072
	ds_read_b128 v[192:195], v179 offset:320
	ds_read_b128 v[196:199], v204 offset:45312
	ds_read_b128 v[200:203], v204 offset:45376
	ds_read_b128 v[216:219], v179 offset:384
	ds_read_b128 v[220:223], v204 offset:47616
	ds_read_b128 v[224:227], v204 offset:47680
	ds_read_b128 v[228:231], v179 offset:448
	ds_read_b128 v[232:235], v204 offset:49920
	ds_read_b128 v[236:239], v204 offset:49984
	s_waitcnt lgkmcnt(11)
	v_pk_mul_f32 v[60:61], v[60:61], v[180:181]
	v_pk_mul_f32 v[62:63], v[62:63], v[182:183]
	s_waitcnt lgkmcnt(8)
	v_pk_mul_f32 v[48:49], v[48:49], v[192:193]
	v_pk_mul_f32 v[50:51], v[50:51], v[194:195]
	s_waitcnt lgkmcnt(5)
	v_pk_mul_f32 v[88:89], v[88:89], v[216:217]
	v_pk_mul_f32 v[90:91], v[90:91], v[218:219]
	s_waitcnt lgkmcnt(2)
	v_pk_mul_f32 v[92:93], v[92:93], v[228:229]
	v_pk_mul_f32 v[94:95], v[94:95], v[230:231]
	v_mfma_f32_16x16x32_bf16 v[60:63], v[184:187], v[116:119], v[60:63]
	v_mfma_f32_16x16x32_bf16 v[48:51], v[196:199], v[116:119], v[48:51]
	v_mfma_f32_16x16x32_bf16 v[88:91], v[220:223], v[116:119], v[88:91]
	s_waitcnt lgkmcnt(1)
	v_mfma_f32_16x16x32_bf16 v[92:95], v[232:235], v[116:119], v[92:95]
	v_mfma_f32_16x16x32_bf16 v[60:63], v[188:191], v[112:115], v[60:63]
	v_mfma_f32_16x16x32_bf16 v[48:51], v[200:203], v[112:115], v[48:51]
	v_mfma_f32_16x16x32_bf16 v[88:91], v[224:227], v[112:115], v[88:91]
	s_waitcnt lgkmcnt(0)
	v_mfma_f32_16x16x32_bf16 v[92:95], v[236:239], v[112:115], v[92:95]
	ds_read_b128 v[180:183], v179 offset:512
	ds_read_b128 v[184:187], v204 offset:52224
	ds_read_b128 v[188:191], v204 offset:52288
	ds_read_b128 v[192:195], v179 offset:576
	ds_read_b128 v[196:199], v204 offset:54528
	ds_read_b128 v[200:203], v204 offset:54592
	ds_read_b128 v[216:219], v179 offset:640
	ds_read_b128 v[220:223], v204 offset:56832
	ds_read_b128 v[224:227], v204 offset:56896
	ds_read_b128 v[228:231], v179 offset:704
	ds_read_b128 v[232:235], v204 offset:59136
	ds_read_b128 v[236:239], v204 offset:59200
	s_waitcnt lgkmcnt(11)
; #define LAS __attribute__((address_space(3)))
; __device__ __forceinline__ bf16_t f2bf(float f) { return (bf16_t)(cvt_pk_bf16(f, 0.f) & 0xffffu); }
; #define LWAIT() do { asm volatile("s_waitcnt lgkmcnt(0)" ::: "memory"); __builtin_amdgcn_sched_barrier(0); } while (0)
; __device__ __forceinline__ void gla_scan_item(ArgsP a, int item, LAS unsigned char* lds) {
;     ...
;         for (int m4 = 0; m4 < 4; ++m4) { bf16x8 av[4][2]; f32x4 dv4[4];
; #pragma unroll
;             for (int q = 0; q < 4; ++q) { const int mt = 4 * m4 + q; dv4[q] = *(const LAS f32x4*)(decl + 16 * mt + 4 * g4);
; #pragma unroll
;                 for (int ks = 0; ks < 2; ++ks) av[q][ks] = *(const LAS bf16x8*)(ktl + (16 * mt + fr) * 144 + (32 * ks + 8 * g4) * 2); }
;             LWAIT();
; #pragma unroll
;             for (int q = 0; q < 4; ++q) S[4 * m4 + q] = S[4 * m4 + q] * dv4[q];
; #pragma unroll
;             for (int ks = 0; ks < 2; ++ks)
; #pragma unroll
;                 for (int q = 0; q < 4; ++q) S[4 * m4 + q] = __builtin_amdgcn_mfma_f32_16x16x32_bf16(av[q][ks], vf[ks], S[4 * m4 + q], 0, 0, 0); }
;     ...
;         bf16_t* op = Obuf + (size_t)base * 2048 + h * 512 + dvs * 128 + 16 * wave + fr;
; #pragma unroll
;         for (int it = 0; it < 4; ++it)
; #pragma unroll
;             for (int r = 0; r < 4; ++r) op[(size_t)(16 * it + 4 * g4 + r) * 2048] = f2bf(o[it][r]);
;     }
	v_pk_mul_f32 v[96:97], v[96:97], v[180:181]
	v_pk_mul_f32 v[98:99], v[98:99], v[182:183]
	s_waitcnt lgkmcnt(8)
	v_pk_mul_f32 v[100:101], v[100:101], v[192:193]
	v_pk_mul_f32 v[102:103], v[102:103], v[194:195]
	s_waitcnt lgkmcnt(5)
	v_pk_mul_f32 v[104:105], v[104:105], v[216:217]
	v_pk_mul_f32 v[106:107], v[106:107], v[218:219]
	s_waitcnt lgkmcnt(2)
	v_pk_mul_f32 v[108:109], v[108:109], v[228:229]
	v_pk_mul_f32 v[110:111], v[110:111], v[230:231]
	v_mfma_f32_16x16x32_bf16 v[96:99], v[184:187], v[116:119], v[96:99]
	v_mfma_f32_16x16x32_bf16 v[100:103], v[196:199], v[116:119], v[100:103]
	v_mfma_f32_16x16x32_bf16 v[104:107], v[220:223], v[116:119], v[104:107]
	s_waitcnt lgkmcnt(1)
	v_mfma_f32_16x16x32_bf16 v[108:111], v[232:235], v[116:119], v[108:111]
	v_mfma_f32_16x16x32_bf16 v[96:99], v[188:191], v[112:115], v[96:99]
	v_mfma_f32_16x16x32_bf16 v[100:103], v[200:203], v[112:115], v[100:103]
	v_mfma_f32_16x16x32_bf16 v[104:107], v[224:227], v[112:115], v[104:107]
	s_waitcnt lgkmcnt(0)
	v_mfma_f32_16x16x32_bf16 v[108:111], v[236:239], v[112:115], v[108:111]
	ds_read_b128 v[180:183], v179 offset:768
	ds_read_b128 v[184:187], v204 offset:61440
	ds_read_b128 v[188:191], v204 offset:61504
	ds_read_b128 v[192:195], v179 offset:832
	ds_read_b128 v[196:199], v204 offset:63744
	ds_read_b128 v[200:203], v204 offset:63808
	ds_read_b128 v[216:219], v179 offset:896
	ds_read_b128 v[220:223], v166 offset:32256
	ds_read_b128 v[224:227], v166 offset:32320
	ds_read_b128 v[228:231], v179 offset:960
	ds_read_b128 v[232:235], v166 offset:34560
	ds_read_b128 v[236:239], v166 offset:34624
	s_waitcnt lgkmcnt(11)
	v_pk_mul_f32 v[84:85], v[84:85], v[180:181]
	v_pk_mul_f32 v[86:87], v[86:87], v[182:183]
	s_waitcnt lgkmcnt(8)
	v_pk_mul_f32 v[52:53], v[52:53], v[192:193]
	v_pk_mul_f32 v[54:55], v[54:55], v[194:195]
	s_waitcnt lgkmcnt(5)
	v_pk_mul_f32 v[56:57], v[56:57], v[216:217]
	v_pk_mul_f32 v[58:59], v[58:59], v[218:219]
	s_waitcnt lgkmcnt(2)
	v_pk_mul_f32 v[64:65], v[64:65], v[228:229]
	v_pk_mul_f32 v[66:67], v[66:67], v[230:231]
	s_ashr_i32 s19, s18, 31
	v_mfma_f32_16x16x32_bf16 v[84:87], v[184:187], v[116:119], v[84:87]
	s_lshl_b64 s[18:19], s[18:19], 12
	s_movk_i32 s17, 0x3000
	s_add_i32 s22, s22, -1
	v_mfma_f32_16x16x32_bf16 v[52:55], v[196:199], v[116:119], v[52:55]
	s_cmp_lg_u32 s22, 2
	s_mov_b32 s35, s23
	v_mfma_f32_16x16x32_bf16 v[56:59], v[220:223], v[116:119], v[56:59]
	s_waitcnt lgkmcnt(1)
	v_mfma_f32_16x16x32_bf16 v[64:67], v[232:235], v[116:119], v[64:67]
	v_cvt_pk_bf16_f32 v118, v132, v161
	v_lshl_add_u64 v[116:117], v[148:149], 0, s[18:19]
	global_store_short v[116:117], v118, off
	v_add_co_u32_e32 v118, vcc, s50, v116
	v_mfma_f32_16x16x32_bf16 v[84:87], v[188:191], v[112:115], v[84:87]
	s_nop 0
	v_addc_co_u32_e32 v119, vcc, 0, v117, vcc
	v_cvt_pk_bf16_f32 v132, v133, v161
	v_mfma_f32_16x16x32_bf16 v[52:55], v[200:203], v[112:115], v[52:55]
	global_store_short v[118:119], v132, off offset:-4096
	v_cvt_pk_bf16_f32 v132, v134, v161
	global_store_short v[118:119], v132, off
	v_mfma_f32_16x16x32_bf16 v[56:59], v[224:227], v[112:115], v[56:59]
	v_cvt_pk_bf16_f32 v118, v135, v161
	s_waitcnt lgkmcnt(0)
	v_mfma_f32_16x16x32_bf16 v[64:67], v[236:239], v[112:115], v[64:67]
	v_add_co_u32_e32 v112, vcc, s17, v116
	s_mov_b32 s17, 0x11000
	s_nop 0
	v_addc_co_u32_e32 v113, vcc, 0, v117, vcc
	global_store_short v[112:113], v118, off
	v_add_co_u32_e32 v112, vcc, s17, v116
	v_cvt_pk_bf16_f32 v114, v128, v161
	s_mov_b32 s17, 0x13000
	s_nop 0
	v_addc_co_u32_e32 v113, vcc, 0, v117, vcc
	global_store_short v[112:113], v114, off offset:-4096
	v_cvt_pk_bf16_f32 v114, v129, v161
	global_store_short v[112:113], v114, off
	v_add_co_u32_e32 v112, vcc, s17, v116
	v_cvt_pk_bf16_f32 v114, v130, v161
	s_mov_b32 s17, 0x21000
	s_nop 0
	v_addc_co_u32_e32 v113, vcc, 0, v117, vcc
	global_store_short v[112:113], v114, off offset:-4096
	v_cvt_pk_bf16_f32 v114, v131, v161
	global_store_short v[112:113], v114, off
	v_add_co_u32_e32 v112, vcc, s17, v116
	v_cvt_pk_bf16_f32 v114, v124, v161
	s_mov_b32 s17, 0x23000
	s_nop 0
	v_addc_co_u32_e32 v113, vcc, 0, v117, vcc
	global_store_short v[112:113], v114, off offset:-4096
	v_cvt_pk_bf16_f32 v114, v125, v161
	global_store_short v[112:113], v114, off
	v_add_co_u32_e32 v112, vcc, s17, v116
	v_cvt_pk_bf16_f32 v114, v126, v161
	s_mov_b32 s17, 0x31000
	s_nop 0
	v_addc_co_u32_e32 v113, vcc, 0, v117, vcc
	global_store_short v[112:113], v114, off offset:-4096
	v_cvt_pk_bf16_f32 v114, v127, v161
	global_store_short v[112:113], v114, off
	v_add_co_u32_e32 v112, vcc, s17, v116
	v_cvt_pk_bf16_f32 v114, v120, v161
	s_mov_b32 s17, 0x33000
	s_nop 0
	v_addc_co_u32_e32 v113, vcc, 0, v117, vcc
	global_store_short v[112:113], v114, off offset:-4096
	v_cvt_pk_bf16_f32 v114, v121, v161
	global_store_short v[112:113], v114, off
	v_add_co_u32_e32 v112, vcc, s17, v116
	v_cvt_pk_bf16_f32 v114, v122, v161
	s_nop 1
	v_addc_co_u32_e32 v113, vcc, 0, v117, vcc
	global_store_short v[112:113], v114, off offset:-4096
	v_cvt_pk_bf16_f32 v114, v123, v161
	global_store_short v[112:113], v114, off
	s_cbranch_scc0 .LBB0_1310
